# conv gain loops: two source iterations (16 gain + 16 weight loads) in flight per trip; first-barrier census: 16 counter loads issued together
# speedup vs baseline: 1.0147x; 1.0009x over previous
; #define LAS __attribute__((address_space(3)))
; __device__ __forceinline__ void conv_item(const float* W, int Nsrc, int K, int k0, int scol, bf16_t* WT, int drow, const float* gain, float cscale, LAS float* scr, int lane) {
; #pragma unroll 8
;     for (int i = 0; i < 32; ++i) { const int kk = 2 * i + (lane >> 5); const float gg = gain ? gain[k0 + kk] * cscale : cscale;
;         scr[kk * 33 + (lane & 31)] = W[(size_t)(k0 + kk) * Nsrc + scol + (lane & 31)] * gg; }
;     asm volatile("s_waitcnt lgkmcnt(0)" ::: "memory");
; __device__ __forceinline__ void conv_layer(const Args& a, int l, bf16_t* WB, LAS unsigned char* lds, int ngw) {
;     ...
;         if (r < I4) { const int gi = r / 512, rr = r % 512, kb = rr / 32, db = rr % 32;
;             conv_item(a.w_gate + ((size_t)l * 3 + gi) * 1024 * 1024, 1024, 1024, kb * 64, db * 32, WB + WO_WG, gi * 1024 + db * 32, a.norm_mix + l * 1024, 1.f, scr, lane);
;             continue; }
.Lcv37_loop:
	v_lshl_add_u64 v[142:143], s[28:29], 0, v[0:1]
	v_lshl_add_u64 v[144:145], s[28:29], 0, v[28:29]
	global_load_dword v110, v[142:143], off offset:-56
	global_load_dword v111, v[144:145], off offset:-48
	global_load_dword v112, v[144:145], off offset:-40
	global_load_dword v113, v[144:145], off offset:-32
	global_load_dword v114, v[144:145], off offset:-24
	global_load_dword v115, v[144:145], off offset:-16
	global_load_dword v116, v[144:145], off offset:-8
	global_load_dword v117, v[144:145], off
	global_load_dword v118, v[142:143], off offset:8
	global_load_dword v119, v[144:145], off offset:16
	global_load_dword v120, v[144:145], off offset:24
	global_load_dword v121, v[144:145], off offset:32
	global_load_dword v122, v[144:145], off offset:40
	global_load_dword v123, v[144:145], off offset:48
	global_load_dword v124, v[144:145], off offset:56
	global_load_dword v125, v[144:145], off offset:64
	s_add_u32 s38, s0, 0x10000
	s_addc_u32 s39, s1, 0
	v_lshl_add_u64 v[150:151], v[42:43], 0, s[0:1]
	v_lshl_add_u64 v[152:153], v[40:41], 0, s[0:1]
	v_lshl_add_u64 v[154:155], v[38:39], 0, s[0:1]
	v_lshl_add_u64 v[156:157], v[36:37], 0, s[0:1]
	v_lshl_add_u64 v[158:159], v[34:35], 0, s[0:1]
	v_lshl_add_u64 v[160:161], v[32:33], 0, s[0:1]
	v_lshl_add_u64 v[162:163], v[30:31], 0, s[0:1]
	v_lshl_add_u64 v[164:165], v[26:27], 0, s[0:1]
	v_lshl_add_u64 v[166:167], v[42:43], 0, s[38:39]
	v_lshl_add_u64 v[168:169], v[40:41], 0, s[38:39]
	v_lshl_add_u64 v[170:171], v[38:39], 0, s[38:39]
	v_lshl_add_u64 v[172:173], v[36:37], 0, s[38:39]
	v_lshl_add_u64 v[174:175], v[34:35], 0, s[38:39]
	v_lshl_add_u64 v[176:177], v[32:33], 0, s[38:39]
	v_lshl_add_u64 v[178:179], v[30:31], 0, s[38:39]
	v_lshl_add_u64 v[180:181], v[26:27], 0, s[38:39]
	global_load_dword v126, v[150:151], off
	global_load_dword v127, v[152:153], off
	global_load_dword v128, v[154:155], off
	global_load_dword v129, v[156:157], off
	global_load_dword v130, v[158:159], off
	global_load_dword v131, v[160:161], off
	global_load_dword v132, v[162:163], off
	global_load_dword v133, v[164:165], off
	global_load_dword v134, v[166:167], off
	global_load_dword v135, v[168:169], off
	global_load_dword v136, v[170:171], off
	global_load_dword v137, v[172:173], off
	global_load_dword v138, v[174:175], off
	global_load_dword v139, v[176:177], off
	global_load_dword v140, v[178:179], off
	global_load_dword v141, v[180:181], off
	s_waitcnt vmcnt(15)
	v_mul_f32_e32 v110, v110, v126
	ds_write_b32 v46, v110
	s_waitcnt vmcnt(14)
	v_mul_f32_e32 v111, v111, v127
	ds_write_b32 v46, v111 offset:264
	s_waitcnt vmcnt(13)
	v_mul_f32_e32 v112, v112, v128
	ds_write_b32 v46, v112 offset:528
	s_waitcnt vmcnt(12)
	v_mul_f32_e32 v113, v113, v129
	ds_write_b32 v46, v113 offset:792
	s_waitcnt vmcnt(11)
	v_mul_f32_e32 v114, v114, v130
	ds_write_b32 v46, v114 offset:1056
	s_waitcnt vmcnt(10)
	v_mul_f32_e32 v115, v115, v131
	ds_write_b32 v46, v115 offset:1320
	s_waitcnt vmcnt(9)
	v_mul_f32_e32 v116, v116, v132
	ds_write_b32 v46, v116 offset:1584
	s_waitcnt vmcnt(8)
	v_mul_f32_e32 v117, v117, v133
	ds_write_b32 v46, v117 offset:1848
	s_waitcnt vmcnt(7)
	v_mul_f32_e32 v118, v118, v134
	ds_write_b32 v46, v118 offset:2112
	s_waitcnt vmcnt(6)
	v_mul_f32_e32 v119, v119, v135
	ds_write_b32 v46, v119 offset:2376
	s_waitcnt vmcnt(5)
	v_mul_f32_e32 v120, v120, v136
	ds_write_b32 v46, v120 offset:2640
	s_waitcnt vmcnt(4)
	v_mul_f32_e32 v121, v121, v137
	ds_write_b32 v46, v121 offset:2904
	s_waitcnt vmcnt(3)
	v_mul_f32_e32 v122, v122, v138
	ds_write_b32 v46, v122 offset:3168
	s_waitcnt vmcnt(2)
	v_mul_f32_e32 v123, v123, v139
	ds_write_b32 v46, v123 offset:3432
	s_waitcnt vmcnt(1)
	v_mul_f32_e32 v124, v124, v140
	ds_write_b32 v46, v124 offset:3696
	s_waitcnt vmcnt(0)
	v_mul_f32_e32 v125, v125, v141
	ds_write_b32 v46, v125 offset:3960
	s_add_u32 s0, s0, 0x20000
	s_addc_u32 s1, s1, 0
	s_add_u32 s28, s28, 0x80
	s_addc_u32 s29, s29, 0
	v_add_u32_e32 v46, 0x1080, v46
	s_cmp_lg_u32 s0, 0x40000
	s_cbranch_scc1 .Lcv37_loop
	s_branch .LBB0_53

; #define LAS __attribute__((address_space(3)))
; __device__ __forceinline__ void conv_item(const float* W, int Nsrc, int K, int k0, int scol, bf16_t* WT, int drow, const float* gain, float cscale, LAS float* scr, int lane) {
; #pragma unroll 8
;     for (int i = 0; i < 32; ++i) { const int kk = 2 * i + (lane >> 5); const float gg = gain ? gain[k0 + kk] * cscale : cscale;
;         scr[kk * 33 + (lane & 31)] = W[(size_t)(k0 + kk) * Nsrc + scol + (lane & 31)] * gg; }
;     asm volatile("s_waitcnt lgkmcnt(0)" ::: "memory");
; __device__ __forceinline__ void conv_layer(const Args& a, int l, bf16_t* WB, LAS unsigned char* lds, int ngw) {
;     ...
;         if (r < I3) { const int kb = r / 120, db = r % 120, col = db * 32;
;             const bool isq = col < 512 || (col >= 1536 && col < 2048) || (col >= 3072 && col < 3584);
;             conv_item(a.w_in + (size_t)l * 1024 * INC, INC, 1024, kb * 64, col, WB + WO_WIN, col, a.norm_mix + l * 1024, isq ? 0.125f * LOG2E : 1.f, scr, lane);
;             continue; }
.Lcv58_loop:
	v_lshl_add_u64 v[142:143], s[28:29], 0, v[0:1]
	v_lshl_add_u64 v[144:145], s[28:29], 0, v[28:29]
	global_load_dword v110, v[142:143], off offset:-56
	global_load_dword v111, v[144:145], off offset:-48
	global_load_dword v112, v[144:145], off offset:-40
	global_load_dword v113, v[144:145], off offset:-32
	global_load_dword v114, v[144:145], off offset:-24
	global_load_dword v115, v[144:145], off offset:-16
	global_load_dword v116, v[144:145], off offset:-8
	global_load_dword v117, v[144:145], off
	global_load_dword v118, v[142:143], off offset:8
	global_load_dword v119, v[144:145], off offset:16
	global_load_dword v120, v[144:145], off offset:24
	global_load_dword v121, v[144:145], off offset:32
	global_load_dword v122, v[144:145], off offset:40
	global_load_dword v123, v[144:145], off offset:48
	global_load_dword v124, v[144:145], off offset:56
	global_load_dword v125, v[144:145], off offset:64
	s_add_u32 s38, s0, 0x3c000
	s_addc_u32 s39, s1, 0
	v_lshl_add_u64 v[150:151], v[42:43], 0, s[0:1]
	v_lshl_add_u64 v[152:153], v[40:41], 0, s[0:1]
	v_lshl_add_u64 v[154:155], v[38:39], 0, s[0:1]
	v_lshl_add_u64 v[156:157], v[36:37], 0, s[0:1]
	v_lshl_add_u64 v[158:159], v[34:35], 0, s[0:1]
	v_lshl_add_u64 v[160:161], v[32:33], 0, s[0:1]
	v_lshl_add_u64 v[162:163], v[30:31], 0, s[0:1]
	v_lshl_add_u64 v[164:165], v[26:27], 0, s[0:1]
	v_lshl_add_u64 v[166:167], v[42:43], 0, s[38:39]
	v_lshl_add_u64 v[168:169], v[40:41], 0, s[38:39]
	v_lshl_add_u64 v[170:171], v[38:39], 0, s[38:39]
	v_lshl_add_u64 v[172:173], v[36:37], 0, s[38:39]
	v_lshl_add_u64 v[174:175], v[34:35], 0, s[38:39]
	v_lshl_add_u64 v[176:177], v[32:33], 0, s[38:39]
	v_lshl_add_u64 v[178:179], v[30:31], 0, s[38:39]
	v_lshl_add_u64 v[180:181], v[26:27], 0, s[38:39]
	global_load_dword v126, v[150:151], off
	global_load_dword v127, v[152:153], off
	global_load_dword v128, v[154:155], off
	global_load_dword v129, v[156:157], off
	global_load_dword v130, v[158:159], off
	global_load_dword v131, v[160:161], off
	global_load_dword v132, v[162:163], off
	global_load_dword v133, v[164:165], off
	global_load_dword v134, v[166:167], off
	global_load_dword v135, v[168:169], off
	global_load_dword v136, v[170:171], off
	global_load_dword v137, v[172:173], off
	global_load_dword v138, v[174:175], off
	global_load_dword v139, v[176:177], off
	global_load_dword v140, v[178:179], off
	global_load_dword v141, v[180:181], off
	s_waitcnt vmcnt(15)
	v_mul_f32_e32 v110, v46, v110
	v_mul_f32_e32 v110, v110, v126
	ds_write_b32 v47, v110
	s_waitcnt vmcnt(14)
	v_mul_f32_e32 v111, v46, v111
	v_mul_f32_e32 v111, v111, v127
	ds_write_b32 v47, v111 offset:264
	s_waitcnt vmcnt(13)
	v_mul_f32_e32 v112, v46, v112
	v_mul_f32_e32 v112, v112, v128
	ds_write_b32 v47, v112 offset:528
	s_waitcnt vmcnt(12)
	v_mul_f32_e32 v113, v46, v113
	v_mul_f32_e32 v113, v113, v129
	ds_write_b32 v47, v113 offset:792
	s_waitcnt vmcnt(11)
	v_mul_f32_e32 v114, v46, v114
	v_mul_f32_e32 v114, v114, v130
	ds_write_b32 v47, v114 offset:1056
	s_waitcnt vmcnt(10)
	v_mul_f32_e32 v115, v46, v115
	v_mul_f32_e32 v115, v115, v131
	ds_write_b32 v47, v115 offset:1320
	s_waitcnt vmcnt(9)
	v_mul_f32_e32 v116, v46, v116
	v_mul_f32_e32 v116, v116, v132
	ds_write_b32 v47, v116 offset:1584
	s_waitcnt vmcnt(8)
	v_mul_f32_e32 v117, v46, v117
	v_mul_f32_e32 v117, v117, v133
	ds_write_b32 v47, v117 offset:1848
	s_waitcnt vmcnt(7)
	v_mul_f32_e32 v118, v46, v118
	v_mul_f32_e32 v118, v118, v134
	ds_write_b32 v47, v118 offset:2112
	s_waitcnt vmcnt(6)
	v_mul_f32_e32 v119, v46, v119
	v_mul_f32_e32 v119, v119, v135
	ds_write_b32 v47, v119 offset:2376
	s_waitcnt vmcnt(5)
	v_mul_f32_e32 v120, v46, v120
	v_mul_f32_e32 v120, v120, v136
	ds_write_b32 v47, v120 offset:2640
	s_waitcnt vmcnt(4)
	v_mul_f32_e32 v121, v46, v121
	v_mul_f32_e32 v121, v121, v137
	ds_write_b32 v47, v121 offset:2904
	s_waitcnt vmcnt(3)
	v_mul_f32_e32 v122, v46, v122
	v_mul_f32_e32 v122, v122, v138
	ds_write_b32 v47, v122 offset:3168
	s_waitcnt vmcnt(2)
	v_mul_f32_e32 v123, v46, v123
	v_mul_f32_e32 v123, v123, v139
	ds_write_b32 v47, v123 offset:3432
	s_waitcnt vmcnt(1)
	v_mul_f32_e32 v124, v46, v124
	v_mul_f32_e32 v124, v124, v140
	ds_write_b32 v47, v124 offset:3696
	s_waitcnt vmcnt(0)
	v_mul_f32_e32 v125, v46, v125
	v_mul_f32_e32 v125, v125, v141
	ds_write_b32 v47, v125 offset:3960
	s_add_u32 s0, s0, 0x78000
	s_addc_u32 s1, s1, 0
	s_add_u32 s28, s28, 0x80
	s_addc_u32 s29, s29, 0
	v_add_u32_e32 v47, 0x1080, v47
	s_cmp_lg_u32 s0, 0xf0000
	s_cbranch_scc1 .Lcv58_loop
	s_branch .LBB0_74

; #define LAS __attribute__((address_space(3)))
; __device__ __forceinline__ void conv_item(const float* W, int Nsrc, int K, int k0, int scol, bf16_t* WT, int drow, const float* gain, float cscale, LAS float* scr, int lane) {
; #pragma unroll 8
;     for (int i = 0; i < 32; ++i) { const int kk = 2 * i + (lane >> 5); const float gg = gain ? gain[k0 + kk] * cscale : cscale;
;         scr[kk * 33 + (lane & 31)] = W[(size_t)(k0 + kk) * Nsrc + scol + (lane & 31)] * gg; }
;     asm volatile("s_waitcnt lgkmcnt(0)" ::: "memory");
; __device__ __forceinline__ void conv_layer(const Args& a, int l, bf16_t* WB, LAS unsigned char* lds, int ngw) {
;     ...
;         if (r < I1 || (r >= I1 + I2 + I3 + I4 + I5 + I6 && r < I1 + I2 + I3 + I4 + I5 + I6 + I1)) {
;             const bool second = r >= I1; if (second) r -= I1 + I2 + I3 + I4 + I5 + I6;
;             const int kb = r / 176, db = r % 176, pn = db >> 3, o8 = db & 7; const int scol = (o8 >> 2) * DFF + 128 * pn + (o8 & 3) * 32;
;             conv_item((second ? a.w_ffn2_in : a.w_ffn1_in) + (size_t)l * 1024 * 5632, 5632, 1024, kb * 64, scol, WB + (second ? WO_W3 : WO_W1), db * 32, (second ? a.norm_ffn2 : a.norm_ffn1) + l * 1024, 1.f, scr, lane);
;             continue; }
.Lcv84_loop:
	v_lshl_add_u64 v[142:143], s[40:41], 0, v[42:43]
	v_lshl_add_u64 v[144:145], s[40:41], 0, v[28:29]
	global_load_dword v110, v[142:143], off offset:-56
	global_load_dword v111, v[144:145], off offset:-48
	global_load_dword v112, v[144:145], off offset:-40
	global_load_dword v113, v[144:145], off offset:-32
	global_load_dword v114, v[144:145], off offset:-24
	global_load_dword v115, v[144:145], off offset:-16
	global_load_dword v116, v[144:145], off offset:-8
	global_load_dword v117, v[144:145], off
	global_load_dword v118, v[142:143], off offset:8
	global_load_dword v119, v[144:145], off offset:16
	global_load_dword v120, v[144:145], off offset:24
	global_load_dword v121, v[144:145], off offset:32
	global_load_dword v122, v[144:145], off offset:40
	global_load_dword v123, v[144:145], off offset:48
	global_load_dword v124, v[144:145], off offset:56
	global_load_dword v125, v[144:145], off offset:64
	s_add_u32 s38, s30, 0x58000
	s_addc_u32 s39, s31, 0
	v_lshl_add_u64 v[150:151], v[44:45], 0, s[30:31]
	v_lshl_add_u64 v[152:153], v[40:41], 0, s[30:31]
	v_lshl_add_u64 v[154:155], v[38:39], 0, s[30:31]
	v_lshl_add_u64 v[156:157], v[36:37], 0, s[30:31]
	v_lshl_add_u64 v[158:159], v[34:35], 0, s[30:31]
	v_lshl_add_u64 v[160:161], v[32:33], 0, s[30:31]
	v_lshl_add_u64 v[162:163], v[30:31], 0, s[30:31]
	v_lshl_add_u64 v[164:165], v[26:27], 0, s[30:31]
	v_lshl_add_u64 v[166:167], v[44:45], 0, s[38:39]
	v_lshl_add_u64 v[168:169], v[40:41], 0, s[38:39]
	v_lshl_add_u64 v[170:171], v[38:39], 0, s[38:39]
	v_lshl_add_u64 v[172:173], v[36:37], 0, s[38:39]
	v_lshl_add_u64 v[174:175], v[34:35], 0, s[38:39]
	v_lshl_add_u64 v[176:177], v[32:33], 0, s[38:39]
	v_lshl_add_u64 v[178:179], v[30:31], 0, s[38:39]
	v_lshl_add_u64 v[180:181], v[26:27], 0, s[38:39]
	global_load_dword v126, v[150:151], off
	global_load_dword v127, v[152:153], off
	global_load_dword v128, v[154:155], off
	global_load_dword v129, v[156:157], off
	global_load_dword v130, v[158:159], off
	global_load_dword v131, v[160:161], off
	global_load_dword v132, v[162:163], off
	global_load_dword v133, v[164:165], off
	global_load_dword v134, v[166:167], off
	global_load_dword v135, v[168:169], off
	global_load_dword v136, v[170:171], off
	global_load_dword v137, v[172:173], off
	global_load_dword v138, v[174:175], off
	global_load_dword v139, v[176:177], off
	global_load_dword v140, v[178:179], off
	global_load_dword v141, v[180:181], off
	s_waitcnt vmcnt(15)
	v_mul_f32_e32 v110, v110, v126
	ds_write_b32 v0, v110
	s_waitcnt vmcnt(14)
	v_mul_f32_e32 v111, v111, v127
	ds_write_b32 v0, v111 offset:264
	s_waitcnt vmcnt(13)
	v_mul_f32_e32 v112, v112, v128
	ds_write_b32 v0, v112 offset:528
	s_waitcnt vmcnt(12)
	v_mul_f32_e32 v113, v113, v129
	ds_write_b32 v0, v113 offset:792
	s_waitcnt vmcnt(11)
	v_mul_f32_e32 v114, v114, v130
	ds_write_b32 v0, v114 offset:1056
	s_waitcnt vmcnt(10)
	v_mul_f32_e32 v115, v115, v131
	ds_write_b32 v0, v115 offset:1320
	s_waitcnt vmcnt(9)
	v_mul_f32_e32 v116, v116, v132
	ds_write_b32 v0, v116 offset:1584
	s_waitcnt vmcnt(8)
	v_mul_f32_e32 v117, v117, v133
	ds_write_b32 v0, v117 offset:1848
	s_waitcnt vmcnt(7)
	v_mul_f32_e32 v118, v118, v134
	ds_write_b32 v0, v118 offset:2112
	s_waitcnt vmcnt(6)
	v_mul_f32_e32 v119, v119, v135
	ds_write_b32 v0, v119 offset:2376
	s_waitcnt vmcnt(5)
	v_mul_f32_e32 v120, v120, v136
	ds_write_b32 v0, v120 offset:2640
	s_waitcnt vmcnt(4)
	v_mul_f32_e32 v121, v121, v137
	ds_write_b32 v0, v121 offset:2904
	s_waitcnt vmcnt(3)
	v_mul_f32_e32 v122, v122, v138
	ds_write_b32 v0, v122 offset:3168
	s_waitcnt vmcnt(2)
	v_mul_f32_e32 v123, v123, v139
	ds_write_b32 v0, v123 offset:3432
	s_waitcnt vmcnt(1)
	v_mul_f32_e32 v124, v124, v140
	ds_write_b32 v0, v124 offset:3696
	s_waitcnt vmcnt(0)
	v_mul_f32_e32 v125, v125, v141
	ds_write_b32 v0, v125 offset:3960
	s_add_u32 s30, s30, 0xb0000
	s_addc_u32 s31, s31, 0
	s_add_u32 s40, s40, 0x80
	s_addc_u32 s41, s41, 0
	v_add_u32_e32 v0, 0x1080, v0
	s_cmp_lg_u32 s30, 0x160000
	s_cbranch_scc1 .Lcv84_loop
	s_branch .LBB0_19

; __device__ __forceinline__ unsigned xb_ld(unsigned* p)              { return __hip_atomic_load(p, __ATOMIC_RELAXED, __HIP_MEMORY_SCOPE_AGENT); }
; __device__ __forceinline__ void xcd_barrier_complete(unsigned* bar, unsigned x, unsigned& nloc, unsigned& nx) {
;     ...
;     for (;;) {
;         sum = 0u; cnt = 0u; mine = 0u;
; #pragma unroll
;         for (unsigned j = 0; j < 16; ++j) { const unsigned c = xb_ld(&bar[XB_XCNT(j)]); sum += c; cnt += (c > 0u) ? 1u : 0u; mine = (j == x) ? c : mine; }
;         if (sum == G) break;
.LBB0_116:
	v_readlane_b32 s14, v255, 43
	v_readlane_b32 s15, v255, 44
	s_waitcnt lgkmcnt(0)
	global_load_dword v2, v1, s[84:85] sc1
	global_load_dword v0, v1, s[92:93] sc1
	v_readlane_b32 s13, v252, 39
	s_mov_b64 s[28:29], -1
	s_mov_b64 s[30:31], -1
	global_load_dword v3, v1, s[14:15] sc1
	v_readlane_b32 s14, v252, 40
	v_readlane_b32 s15, v252, 41
	s_nop 0
	s_nop 0
	s_nop 2
	global_load_dword v4, v1, s[14:15] sc1
	v_readlane_b32 s14, v252, 42
	v_readlane_b32 s15, v252, 43
	s_nop 0
	s_nop 0
	s_nop 0
	s_nop 0
	s_nop 0
	global_load_dword v5, v1, s[14:15] sc1
	v_readlane_b32 s14, v252, 44
	v_readlane_b32 s15, v252, 45
	s_nop 0
	s_nop 0
	s_nop 2
	global_load_dword v6, v1, s[14:15] sc1
	v_readlane_b32 s14, v252, 46
	v_readlane_b32 s15, v252, 47
	s_nop 0
	s_nop 0
	s_nop 2
	global_load_dword v7, v1, s[14:15] sc1
	v_readlane_b32 s14, v252, 48
	v_readlane_b32 s15, v252, 49
	s_nop 0
	s_nop 0
	s_nop 2
	global_load_dword v8, v1, s[14:15] sc1
	v_readlane_b32 s14, v252, 50
	v_readlane_b32 s15, v252, 51
	s_nop 0
	s_nop 0
	s_nop 2
	global_load_dword v9, v1, s[14:15] sc1
	v_readlane_b32 s14, v252, 52
	v_readlane_b32 s15, v252, 53
	s_nop 0
	s_nop 0
	s_nop 2
	global_load_dword v10, v1, s[14:15] sc1
	v_readlane_b32 s14, v252, 54
	v_readlane_b32 s15, v252, 55
	s_nop 0
	s_nop 0
	s_nop 2
	global_load_dword v11, v1, s[14:15] sc1
	v_readlane_b32 s14, v252, 56
	v_readlane_b32 s15, v252, 57
	s_nop 0
	s_nop 0
	s_nop 2
	global_load_dword v12, v1, s[14:15] sc1
	v_readlane_b32 s14, v252, 58
	v_readlane_b32 s15, v252, 59
	s_nop 0
	s_nop 0
	s_nop 2
	global_load_dword v13, v1, s[14:15] sc1
	v_readlane_b32 s14, v252, 60
	v_readlane_b32 s15, v252, 61
	s_nop 0
	s_nop 0
	s_nop 2
	global_load_dword v14, v1, s[14:15] sc1
	v_readlane_b32 s14, v252, 62
	v_readlane_b32 s15, v252, 63
	s_nop 0
	s_nop 0
	s_nop 2
	global_load_dword v15, v1, s[14:15] sc1
	v_readlane_b32 s14, v253, 0
	v_readlane_b32 s15, v253, 1
	s_nop 0
	s_nop 0
	s_nop 2
	global_load_dword v16, v1, s[14:15] sc1
	s_nop 0
	s_nop 0
	s_waitcnt vmcnt(0)
	v_add_u32_e32 v17, v0, v2
	v_add_u32_e32 v17, v17, v3
	v_add_u32_e32 v17, v17, v4
	v_add_u32_e32 v17, v17, v5
	v_add_u32_e32 v17, v17, v6
	v_add_u32_e32 v17, v17, v7
	v_add_u32_e32 v17, v17, v8
	v_add_u32_e32 v17, v17, v9
	v_add_u32_e32 v17, v17, v10
	v_add_u32_e32 v17, v17, v11
	v_add_u32_e32 v17, v17, v12
	v_add_u32_e32 v17, v17, v13
	v_add_u32_e32 v17, v17, v14
	v_add_u32_e32 v17, v17, v15
	v_add_u32_e32 v17, v17, v16
	v_cmp_eq_u32_e32 vcc, s13, v17
	s_cbranch_vccnz .LBB0_115
	s_and_b32 s13, s12, 0xff
	s_cmp_eq_u32 s13, 0
	s_mov_b64 s[34:35], -1
	s_sleep 1
	s_cbranch_scc1 .LBB0_120
	s_and_b64 vcc, exec, s[34:35]
	s_cbranch_vccz .LBB0_115
